# v49 + even-B prompt tile VALU trim: hoisted lane^32 shuffle address, bias tuple init via v_mov_b64, redundant accumulator-shift moves removed (-21 instr per tile)
# baseline (speedup 1.0000x reference)
; #define LAS __attribute__((address_space(3)))
;     unsigned char* ws = p.ws;
;     unsigned* headP = (unsigned*)(ws + WS_CTL) + CW_QUEUE + 64 * qsel; unsigned* headS = headP + 32;
;     volatile LAS unsigned* slot = (volatile LAS unsigned*)(lds + LDSCTL_OFF + 128);
;     const bf16* QB = (const bf16*)(ws + WS_QB); const bf16* KB = (const bf16*)(ws + WS_KB); const bf16* VT = (const bf16*)(ws + WS_VT); const bf16* VS = (const bf16*)(ws + WS_VS); bf16* AO = (bf16*)(ws + WS_AO);
;     const float* ck = (const float*)p.in[I_CK]; const float* cv = (const float*)p.in[I_CV];
;     typedef const __attribute__((address_space(4))) int* cint_p;
;     constexpr unsigned N_ATT = NB_P * SBH * 16, N_FIX = NB_P * 64, N_PQ = N_ATT + N_FIX, N_SQ = 2 * NB_S;
;     constexpr int KLD = 72, VLD = 68, KBUF = 64 * KLD * 2, VBUF = 64 * VLD * 2;
;     LAS unsigned char* kl = lds; LAS unsigned char* vl = lds + 2 * KBUF;
;     LAS float* xo = (LAS float*)(lds + 36864); LAS float* xp = (LAS float*)(lds + 36864 + 32768);
;     int tid = tid_; asm volatile("" : "+v"(tid));
;     const int lane = tid & 63, r = lane & 31, h2 = lane >> 5;
;     bool pAct = false, pEmpty = (p.mode == 1); int pb = 0, ph = 0, Q0 = 0, kt = 0, cur = 0;
;     bf16x8 qf[4]; f32x16 accO[2]; float pcarry = 1.f, pbias2 = 0.f; u32x4 kr0, vr0, kr1, vr1;
;     const int srow = tid >> 3, sch = tid & 7, kdst = srow * (KLD * 2) + sch * 16, vdst = srow * (VLD * 2) + sch * 16;
;     const bf16* ksrc = KB; const bf16* vsrc = VT;
;     bool sAct = false, sEmpty = (p.mode == 2); int ss = 0, shalf = 0, st = 0;
;     const int hg = wave & 1, seg = wave >> 1, hh = lane >> 4, c = lane & 15, sh = 4 * hg + hh, qme = 2 * (c & 1) + ((c >> 1) & 1);
;     const float sbias2 = ((const float*)p.in[I_SBB])[sh] * LOG2E;
;     LAS f32x4* sq = (LAS f32x4*)(lds + 36864 + 40960) + wave * 256 + lane;
;     SmpAcc A; SmpKV R0, R1; cint_p spt = (cint_p)(unsigned long long)p.in[I_PT];
; #pragma unroll
;     for (int i = 0; i < 4; ++i) { qf[i] = (bf16x8){0, 0, 0, 0, 0, 0, 0, 0}; A.acc[i] = (f32x4){0.f, 0.f, 0.f, 0.f}; }
;     A.carry = 1.f;
; #pragma unroll
;     for (int i = 0; i < 16; ++i) { accO[0][i] = 0.f; accO[1][i] = 0.f; }
;     kr0 = (u32x4){0u, 0u, 0u, 0u}; vr0 = kr0; kr1 = kr0; vr1 = kr0;
; #pragma unroll
;     for (int u = 0; u < 4; ++u) { R0.k[u] = (f32x4){0.f, 0.f, 0.f, 0.f}; R0.v[u] = R0.k[u]; R1.k[u] = R0.k[u]; R1.v[u] = R0.k[u]; }
.LBB0_528:
	v_readlane_b32 s8, v244, 3
	s_cmp_lt_i32 s28, 6
	v_readlane_b32 s14, v244, 9
	s_cselect_b64 s[2:3], -1, 0
	v_readlane_b32 s15, v244, 10
	s_add_u32 s0, s14, 0x1a900000
	s_addc_u32 s1, s15, 0
	v_writelane_b32 v243, s0, 24
	v_readlane_b32 s9, v244, 4
	v_readlane_b32 s10, v244, 5
	v_writelane_b32 v243, s1, 25
	v_writelane_b32 v243, s2, 26
	s_and_b64 s[0:1], s[2:3], s[4:5]
	s_andn2_b64 vcc, exec, s[0:1]
	v_writelane_b32 v243, s3, 27
	s_mov_b64 s[0:1], s[28:29]
	s_mov_b32 s2, s30
	v_writelane_b32 v243, s0, 28
	v_readlane_b32 s11, v244, 6
	v_readlane_b32 s12, v244, 7
	v_writelane_b32 v243, s1, 29
	v_writelane_b32 v243, s2, 30
	v_readlane_b32 s13, v244, 8
	v_writelane_b32 v243, s3, 31
	s_cbranch_vccnz .LBB0_657
	v_readlane_b32 s8, v244, 3
	v_readlane_b32 s14, v244, 9
	v_readlane_b32 s15, v244, 10
	s_add_u32 s0, s14, 0x10080
	s_addc_u32 s1, s15, 0
	s_add_u32 s62, s14, 0x18700000
	s_addc_u32 s63, s15, 0
	s_waitcnt vmcnt(0)
	v_mov_b32_e32 v189, v0
	s_bfe_u32 s3, s33, 0x10006
	s_lshl_b32 s2, s3, 2
	v_bfe_u32 v1, v189, 4, 2
	v_or_b32_e32 v8, s2, v1
	v_bfrev_b32_e32 v2, v189
	v_readlane_b32 s36, v244, 43
	v_ashrrev_i32_e32 v4, 30, v2
	v_lshlrev_b32_e32 v2, 2, v8
	v_readlane_b32 s42, v244, 49
	v_readlane_b32 s43, v244, 50
	v_writelane_b32 v243, s97, 32
	v_writelane_b32 v243, s0, 33
	v_readlane_b32 s10, v244, 5
	v_readlane_b32 s11, v244, 6
	v_writelane_b32 v243, s1, 34
	global_load_dword v2, v2, s[42:43]
	s_lshl_b32 s0, s90, 12
	s_add_i32 s0, s0, 0
	v_writelane_b32 v243, s0, 35
	s_add_i32 s0, s0, 0x13000
	s_add_u32 s70, s14, 0x10000
	s_addc_u32 s71, s15, 0
	s_add_u32 s10, s14, 0x19800000
	s_addc_u32 s11, s15, 0
	s_cmp_eq_u32 s30, 2
	v_ashrrev_i32_e32 v184, 3, v189
	v_and_b32_e32 v5, 7, v189
	s_movk_i32 s1, 0x90
	s_cselect_b64 s[4:5], -1, 0
	s_add_u32 s76, s14, 0x17600000
	v_lshlrev_b32_e32 v6, 4, v5
	v_mul_lo_u32 v7, v184, s1
	s_addc_u32 s77, s15, 0
	v_writelane_b32 v243, s4, 36
	s_cmp_eq_u32 s30, 1
	v_add3_u32 v201, 0, v7, v6
	v_writelane_b32 v243, s5, 37
	s_cselect_b64 s[56:57], -1, 0
	s_lshl_b32 s36, s90, 5
	s_and_b32 s4, s90, 0x3fffffe
	v_lshlrev_b32_e32 v190, 3, v5
	v_lshlrev_b32_e32 v5, 2, v189
	s_sub_u32 s4, 0, s4
	v_and_b32_e32 v198, 60, v5
	s_subb_u32 s5, 0, 0
	v_lshlrev_b32_e32 v196, 6, v8
	v_writelane_b32 v243, s4, 38
	v_lshlrev_b32_e32 v10, 1, v198
	v_and_b32_e32 v5, 1, v189
	v_writelane_b32 v243, s5, 39
	s_mov_b64 s[4:5], 0x1a800000
	v_readlane_b32 s9, v244, 4
	v_writelane_b32 v243, s33, 40
	v_and_b32_e32 v187, 63, v189
	v_lshlrev_b32_e32 v188, 2, v187
	s_cmpk_lt_u32 s33, 0x80
	v_lshlrev_b32_e32 v195, 4, v187
	v_lshl_or_b32 v200, s3, 8, v188
	s_cselect_b64 s[16:17], -1, 0
	s_add_i32 s3, 0, 0x11000
	v_add_u32_e32 v222, s3, v195
	v_and_b32_e32 v3, 3, v189
	v_readlane_b32 s12, v244, 7
	v_readlane_b32 s13, v244, 8
	v_bfe_u32 v12, v189, 5, 1
	v_and_b32_e32 v191, 31, v189
	v_readlane_b32 s37, v244, 44
	v_readlane_b32 s38, v244, 45
	v_readlane_b32 s39, v244, 46
	v_readlane_b32 s40, v244, 47
	v_readlane_b32 s41, v244, 48
	v_readlane_b32 s44, v244, 51
	v_readlane_b32 s45, v244, 52
	v_readlane_b32 s46, v244, 53
	v_readlane_b32 s47, v244, 54
	v_readlane_b32 s48, v244, 55
	v_readlane_b32 s49, v244, 56
	v_readlane_b32 s50, v244, 57
	v_readlane_b32 s51, v244, 58
	v_lshlrev_b32_e32 v186, 3, v12
	v_lshl_add_u32 v218, v12, 4, 0
	v_mov_b32_e32 v214, 1.0
	v_mbcnt_lo_u32_b32 v38, -1, 0
	s_mov_b32 s65, 0
	s_mov_b64 s[66:67], 0x10000
	v_add_u32_e32 v197, s0, v195
	v_cmp_eq_u32_e64 s[0:1], 0, v189
	v_ashrrev_i32_e32 v185, 31, v184
	s_mov_b64 s[6:7], 0
	v_mul_u32_u24_e32 v219, 0x90, v191
	v_lshlrev_b32_e32 v206, 2, v12
	v_sub_u32_e32 v220, v218, v186
	v_mul_u32_u24_e32 v221, 0x88, v191
	v_mov_b64_e32 v[210:211], s[10:11]
	v_mov_b64_e32 v[208:209], s[62:63]
	s_waitcnt vmcnt(0)
; #define LAS __attribute__((address_space(3)))
; DI void prompt_tile(const LAS unsigned char* kc, const LAS unsigned char* vc, const bf16x8 (&qf)[4], f32x16 (&accO)[2], float& carry, float bias2, int key0, int Q0, int r, int h2) {
;     ...
;             for (int q = 0; q < 4; ++q) { const f32x2 pr = kp[kb][2 * q] * kp[kb][2 * q + 1]; R[kb][q] = pr.x * pr.y; Rp[kb][q] = __shfl_xor(R[kb][q], 32); }
;     ...
;     bool pAct = false, pEmpty = (p.mode == 1); int pb = 0, ph = 0, Q0 = 0, kt = 0, cur = 0;
;     bf16x8 qf[4]; f32x16 accO[2]; float pcarry = 1.f, pbias2 = 0.f; u32x4 kr0, vr0, kr1, vr1;
;     const int srow = tid >> 3, sch = tid & 7, kdst = srow * (KLD * 2) + sch * 16, vdst = srow * (VLD * 2) + sch * 16;
;     const bf16* ksrc = KB; const bf16* vsrc = VT;
;     bool sAct = false, sEmpty = (p.mode == 2); int ss = 0, shalf = 0, st = 0;
;     const int hg = wave & 1, seg = wave >> 1, hh = lane >> 4, c = lane & 15, sh = 4 * hg + hh, qme = 2 * (c & 1) + ((c >> 1) & 1);
;     const float sbias2 = ((const float*)p.in[I_SBB])[sh] * LOG2E;
;     LAS f32x4* sq = (LAS f32x4*)(lds + 36864 + 40960) + wave * 256 + lane;
;     SmpAcc A; SmpKV R0, R1; cint_p spt = (cint_p)(unsigned long long)p.in[I_PT];
; #pragma unroll
;     for (int i = 0; i < 4; ++i) { qf[i] = (bf16x8){0, 0, 0, 0, 0, 0, 0, 0}; A.acc[i] = (f32x4){0.f, 0.f, 0.f, 0.f}; }
;     A.carry = 1.f;
; #pragma unroll
;     for (int i = 0; i < 16; ++i) { accO[0][i] = 0.f; accO[1][i] = 0.f; }
;     kr0 = (u32x4){0u, 0u, 0u, 0u}; vr0 = kr0; kr1 = kr0; vr1 = kr0;
; #pragma unroll
;     for (int u = 0; u < 4; ++u) { R0.k[u] = (f32x4){0.f, 0.f, 0.f, 0.f}; R0.v[u] = R0.k[u]; R1.k[u] = R0.k[u]; R1.v[u] = R0.k[u]; }
	v_mul_f32_e32 v199, 0x3fb8aa3b, v2
	v_and_b32_e32 v2, -8, v189
	v_sub_u32_e32 v207, v201, v2
	v_mov_b32_e32 v2, 0
	v_mov_b32_e32 v7, v2
	v_lshl_add_u64 v[192:193], s[10:11], 0, v[6:7]
	v_lshlrev_b32_e32 v6, 7, v8
	v_lshl_add_u64 v[8:9], s[62:63], 0, v[6:7]
	v_mov_b32_e32 v11, v2
	v_lshl_add_u64 v[6:7], s[14:15], 0, v[6:7]
	v_lshl_add_u64 v[6:7], v[6:7], 0, v[10:11]
	v_lshl_add_u64 v[204:205], v[6:7], 0, s[4:5]
	v_cmp_eq_u32_e64 s[4:5], 0, v5
	v_and_b32_e32 v5, 2, v189
	v_cmp_eq_u32_e64 s[8:9], 0, v5
	v_mov_b32_e32 v5, v2
	v_mov_b32_e32 v74, v2
	v_writelane_b32 v243, s8, 41
	v_mov_b32_e32 v75, v2
	v_mov_b32_e32 v90, v2
	v_writelane_b32 v243, s9, 42
	v_cmp_gt_u32_e64 s[8:9], 32, v187
	v_mov_b32_e32 v91, v2
	v_mov_b32_e32 v72, v2
	v_writelane_b32 v243, s8, 43
	v_mov_b32_e32 v73, v2
	v_mov_b32_e32 v88, v2
	v_writelane_b32 v243, s9, 44
	s_lshl_b32 s8, s90, 10
	v_writelane_b32 v243, s8, 45
	s_add_i32 s8, s3, s8
	s_or_b32 s3, s90, 6
	v_writelane_b32 v243, s8, 46
	s_lshl_b32 s8, s3, 10
	s_lshl_b32 s3, s3, 12
	v_writelane_b32 v243, s8, 47
	s_add_i32 s3, s3, 0
	v_writelane_b32 v243, s3, 48
	s_or_b32 s3, s90, 4
	s_lshl_b32 s8, s3, 10
	s_lshl_b32 s3, s3, 12
	v_writelane_b32 v243, s8, 49
	s_add_i32 s3, s3, 0
	v_writelane_b32 v243, s3, 50
	s_mov_b32 s8, s90
	v_writelane_b32 v243, s8, 51
	s_or_b32 s3, s90, 2
	v_mov_b32_e32 v89, v2
	v_writelane_b32 v243, s9, 52
	s_lshl_b32 s8, s3, 10
	s_lshl_b32 s3, s3, 12
	v_writelane_b32 v243, s8, 53
	s_add_i32 s3, s3, 0
	v_writelane_b32 v243, s3, 54
	v_cmp_eq_u32_e64 s[8:9], 0, v187
	s_add_u32 s34, s14, 0x1ea00000
	s_addc_u32 s35, s15, 0
	v_writelane_b32 v243, s8, 55
	s_add_u32 s96, s12, 0x8206000
	s_addc_u32 s97, s13, 0
	v_writelane_b32 v243, s9, 56
	v_cmp_eq_u16_e64 s[8:9], 3, v3
	s_add_u32 s3, s14, 0x29c00000
	v_mov_b64_e32 v[142:143], v[90:91]
	v_writelane_b32 v243, s8, 57
	v_mov_b64_e32 v[126:127], v[90:91]
	v_mov_b64_e32 v[110:111], v[90:91]
	v_writelane_b32 v243, s9, 58
	v_cmp_gt_i16_e64 s[8:9], 0, v4
	v_mov_b32_e32 v4, v2
	v_mov_b64_e32 v[98:99], v[90:91]
	v_writelane_b32 v243, s8, 59
	v_mov_b64_e32 v[150:151], v[90:91]
	v_mov_b64_e32 v[134:135], v[90:91]
	v_writelane_b32 v243, s9, 60
	v_cmp_eq_u16_e64 s[8:9], 0, v3
	v_mov_b32_e32 v3, v2
	v_mov_b64_e32 v[118:119], v[90:91]
	v_writelane_b32 v243, s8, 61
	v_mov_b64_e32 v[102:103], v[90:91]
	v_mov_b64_e32 v[114:115], v[90:91]
	v_writelane_b32 v243, s9, 62
	v_writelane_b32 v243, s3, 63
	s_addc_u32 s3, s15, 0
	s_add_u32 s2, s14, s2
	v_writelane_b32 v242, s3, 0
	s_addc_u32 s3, s15, 0
	s_add_u32 s2, s2, 0x20000
	v_writelane_b32 v242, s2, 1
	s_addc_u32 s2, s3, 0
	v_writelane_b32 v242, s2, 2
	v_writelane_b32 v242, s16, 3
	s_xor_b64 s[12:13], s[16:17], -1
	s_mov_b32 s2, 0
	v_writelane_b32 v242, s17, 4
	v_writelane_b32 v242, s12, 5
	v_mov_b64_e32 v[130:131], v[90:91]
	v_mov_b64_e32 v[146:147], v[90:91]
	v_writelane_b32 v242, s13, 6
	v_readlane_b32 s12, v244, 27
	v_readlane_b32 s13, v244, 28
	v_mov_b64_e32 v[94:95], v[90:91]
	v_writelane_b32 v242, s12, 7
	v_mov_b64_e32 v[106:107], v[90:91]
	v_mov_b64_e32 v[122:123], v[90:91]
	v_writelane_b32 v242, s13, 8
	v_writelane_b32 v242, s2, 9
	v_writelane_b32 v242, s2, 10
	v_mov_b64_e32 v[138:139], v[90:91]
	v_mov_b64_e32 v[154:155], v[90:91]
	v_mov_b64_e32 v[158:159], v[90:91]
	v_mov_b64_e32 v[162:163], v[90:91]
	v_mov_b64_e32 v[166:167], v[90:91]
	v_mov_b64_e32 v[86:87], v[74:75]
	v_mov_b64_e32 v[82:83], v[74:75]
	v_mov_b64_e32 v[78:79], v[74:75]
	v_writelane_b32 v242, s2, 11
	v_mov_b64_e32 v[174:175], v[4:5]
	v_mov_b64_e32 v[170:171], v[4:5]
	v_lshl_add_u64 v[202:203], v[8:9], 0, v[10:11]
	v_mov_b32_e32 v6, v2
	v_mov_b32_e32 v7, v2
	v_mov_b32_e32 v8, v2
	v_mov_b32_e32 v9, v2
	v_mov_b32_e32 v10, v2
	v_mov_b32_e32 v12, v2
	v_mov_b32_e32 v13, v2
	v_mov_b32_e32 v14, v2
	v_mov_b32_e32 v15, v2
	v_mov_b32_e32 v16, v2
	v_mov_b32_e32 v17, v2
	v_mov_b32_e32 v18, v2
	v_mov_b32_e32 v19, v2
	v_mov_b32_e32 v20, v2
	v_mov_b32_e32 v21, v2
	v_mov_b32_e32 v22, v2
	v_mov_b32_e32 v23, v2
	v_mov_b32_e32 v24, v2
	v_mov_b32_e32 v25, v2
	v_mov_b32_e32 v26, v2
	v_mov_b32_e32 v27, v2
	v_mov_b32_e32 v28, v2
	v_mov_b32_e32 v29, v2
	v_mov_b32_e32 v30, v2
	v_mov_b32_e32 v31, v2
	v_mov_b32_e32 v32, v2
	v_mov_b32_e32 v33, v2
	v_mov_b32_e32 v34, v2
	v_mov_b32_e32 v35, v2
	v_mov_b32_e32 v36, v2
	v_mov_b32_e32 v37, v2
	s_add_i32 s51, 0, 0x20080
	s_mov_b32 s45, 0x1a900000
	s_mov_b32 s46, 0xe902000
	s_mov_b32 s33, 0xe903000
	s_mov_b32 s68, 0xe904000
	s_mov_b32 s49, 0x1ca01000
	s_mov_b32 s50, 0x1da01000
	s_mov_b32 s39, 0xe906000
	s_mov_b32 s40, 0xe907000
	s_mov_b32 s41, 0xe908000
	s_mov_b32 s42, 0xe909000
	s_mov_b32 s43, 0x1ca02000
	s_mov_b32 s44, 0x1da02000
	s_mov_b32 s37, 0xe90b000
	s_mov_b32 s47, 0xe90c000
	s_mov_b32 s48, 0xe90d000
	s_mov_b32 s38, 0xe90e000
	s_mov_b32 s3, 0x1ca03000
	s_mov_b32 s10, 0x1da03000
	s_mov_b32 s11, 0xe910000
	s_mov_b32 s78, 0xe911000
	s_mov_b32 s79, 0xe912000
	s_mov_b32 s54, 0xe913000
	s_mov_b32 s55, 0x1a901000
	s_mov_b32 s52, 0x1a902000
	s_mov_b32 s53, 0x1a903000
	s_mov_b32 s58, 0x1a904000
	s_mov_b32 s59, 0x1a905000
	s_mov_b32 s8, 0x1a906000
	s_mov_b32 s9, 0x1a907000
	v_mbcnt_hi_u32_b32 v223, -1, v38
	v_xor_b32_e32 v254, 32, v223
	v_lshlrev_b32_e32 v254, 2, v254
	v_mov_b64_e32 v[140:141], v[88:89]
	v_mov_b64_e32 v[124:125], v[88:89]
	v_mov_b64_e32 v[108:109], v[88:89]
	v_mov_b64_e32 v[96:97], v[88:89]
	v_mov_b64_e32 v[148:149], v[88:89]
	v_mov_b64_e32 v[132:133], v[88:89]
	v_mov_b64_e32 v[116:117], v[88:89]
	v_mov_b64_e32 v[100:101], v[88:89]
	v_mov_b64_e32 v[112:113], v[88:89]
	v_mov_b64_e32 v[128:129], v[88:89]
	v_mov_b64_e32 v[144:145], v[88:89]
	v_mov_b64_e32 v[92:93], v[88:89]
	v_mov_b64_e32 v[104:105], v[88:89]
	v_mov_b64_e32 v[120:121], v[88:89]
	v_mov_b64_e32 v[136:137], v[88:89]
	v_mov_b64_e32 v[152:153], v[88:89]
	v_mov_b64_e32 v[156:157], v[88:89]
	v_mov_b64_e32 v[160:161], v[88:89]
	v_mov_b64_e32 v[164:165], v[88:89]
	v_mov_b64_e32 v[84:85], v[72:73]
	v_mov_b64_e32 v[80:81], v[72:73]
	v_mov_b64_e32 v[76:77], v[72:73]
	v_mov_b32_e32 v213, v214
	v_mov_b64_e32 v[172:173], v[2:3]
	v_mov_b64_e32 v[168:169], v[2:3]
	v_mov_b32_e32 v38, 0
	s_mov_b32 s75, 0
	s_mov_b32 s74, 0
	s_mov_b32 s73, 0
	s_mov_b32 s72, 0
	s_mov_b64 s[60:61], 0
	v_writelane_b32 v242, s96, 12
	v_readlane_b32 s14, v244, 29
	v_readlane_b32 s15, v244, 30
	v_readlane_b32 s16, v244, 31
	v_readlane_b32 s17, v244, 32
	v_readlane_b32 s18, v244, 33
	v_readlane_b32 s19, v244, 34
	v_readlane_b32 s20, v244, 35
	v_readlane_b32 s21, v244, 36
	v_readlane_b32 s22, v244, 37
	v_readlane_b32 s23, v244, 38
	v_readlane_b32 s24, v244, 39
	v_readlane_b32 s25, v244, 40
	v_readlane_b32 s26, v244, 41
	v_readlane_b32 s27, v244, 42
	v_writelane_b32 v242, s97, 13
	s_branch .LBB0_533

; #define LAS __attribute__((address_space(3)))
; DI float fexp2(float x) { return __builtin_amdgcn_exp2f(x); }
; DI float frcp(float x) { return __builtin_amdgcn_rcpf(x); }
; #define MFMA32(a, b, c) __builtin_amdgcn_mfma_f32_32x32x16_bf16((a), (b), (c), 0, 0, 0)
; DI void prompt_tile(const LAS unsigned char* kc, const LAS unsigned char* vc, const bf16x8 (&qf)[4], f32x16 (&accO)[2], float& carry, float bias2, int key0, int Q0, int r, int h2) {
;     constexpr int KLD = 72, VLD = 68;
;     if (key0 < Q0 + 31) {
;         f32x16 sk[2];
; #pragma unroll
;         for (int kb = 0; kb < 2; ++kb) {
; #pragma unroll
;             for (int i = 0; i < 16; ++i) sk[kb][i] = bias2;
; #pragma unroll
;             for (int s = 0; s < 4; ++s) { const bf16x8 a = *(const LAS bf16x8*)(kc + (32 * kb + r) * (KLD * 2) + (16 * s + 8 * h2) * 2); sk[kb] = MFMA32(a, qf[s], sk[kb]); }
;         }
;         const bool need_mask = key0 + 63 >= Q0;
;         f32x2 kp[2][8];
; #pragma unroll
;         for (int kb = 0; kb < 2; ++kb)
; #pragma unroll
;             for (int pq = 0; pq < 8; ++pq) {
;                 f32x2 e2; e2.x = fexp2(sk[kb][2 * pq]); e2.y = fexp2(sk[kb][2 * pq + 1]);
;                 const f32x2 d2 = e2 + 1.0f;
;                 f32x2 k2; k2.x = frcp(d2.x); k2.y = frcp(d2.y);
;                 kp[kb][pq] = k2;
;             }
.LBB0_569:
	s_max_i32 s12, s75, 2
	s_lshl_b32 s12, s12, 6
	s_addk_i32 s12, 0xff80
	s_ashr_i32 s13, s12, 31
	s_lshl_b64 s[14:15], s[12:13], 10
	v_lshl_add_u64 v[4:5], v[208:209], 0, s[14:15]
	global_load_dwordx4 v[176:179], v[4:5], off
	v_lshl_add_u64 v[4:5], s[12:13], 1, v[210:211]
	global_load_dwordx4 v[180:183], v[4:5], off
	v_cndmask_b32_e64 v3, 0, 1, s[60:61]
	v_readlane_b32 s16, v243, 24
	v_cmp_ne_u32_e64 s[18:19], 1, v3
	s_andn2_b64 vcc, exec, s[60:61]
	v_readlane_b32 s17, v243, 25
	s_cbranch_vccnz .LBB0_576
	s_lshl_b32 s12, s75, 6
	s_add_i32 s13, s74, 31
	s_cmp_ge_i32 s12, s13
	s_cbranch_scc1 .LBB0_574
	s_mul_i32 s13, s2, 0x2400
	v_add3_u32 v3, v218, s13, v219
	ds_read_b128 v[224:227], v3
	ds_read_b128 v[228:231], v3 offset:32
	v_mov_b32_e32 v39, v38
	v_mov_b64_e32 v[40:41], v[38:39]
	v_mov_b64_e32 v[42:43], v[38:39]
	v_mov_b64_e32 v[44:45], v[38:39]
	v_mov_b64_e32 v[46:47], v[38:39]
	v_mov_b64_e32 v[48:49], v[38:39]
	v_mov_b64_e32 v[50:51], v[38:39]
	v_mov_b64_e32 v[52:53], v[38:39]
	s_or_b32 s13, s12, 63
	s_cmp_lt_i32 s13, s74
	s_waitcnt lgkmcnt(1)
	v_mfma_f32_32x32x16_bf16 v[56:71], v[224:227], v[72:75], v[38:53]
	ds_read_b128 v[224:227], v3 offset:64
	v_mov_b64_e32 v[54:55], v[52:53]
	s_waitcnt lgkmcnt(1)
	v_mfma_f32_32x32x16_bf16 v[56:71], v[228:231], v[84:87], v[56:71]
	s_waitcnt lgkmcnt(0)
	v_mfma_f32_32x32x16_bf16 v[56:71], v[224:227], v[80:83], v[56:71]
	ds_read_b128 v[224:227], v3 offset:96
	s_waitcnt lgkmcnt(0)
	v_mfma_f32_32x32x16_bf16 v[56:71], v[224:227], v[76:79], v[56:71]
	ds_read_b128 v[224:227], v3 offset:4608
	s_waitcnt lgkmcnt(0)
	v_mfma_f32_32x32x16_bf16 v[40:55], v[224:227], v[72:75], v[40:55]
	ds_read_b128 v[224:227], v3 offset:4640
	s_nop 7
	v_exp_f32_e32 v4, v56
	v_exp_f32_e32 v5, v57
	s_nop 0
	v_pk_add_f32 v[4:5], v[4:5], 1.0 op_sel_hi:[1,0]
	s_waitcnt lgkmcnt(0)
	v_mfma_f32_32x32x16_bf16 v[40:55], v[224:227], v[84:87], v[40:55]
	ds_read_b128 v[224:227], v3 offset:4672
	v_rcp_f32_e32 v56, v4
	v_rcp_f32_e32 v57, v5
	v_exp_f32_e32 v4, v58
	v_exp_f32_e32 v5, v59
	v_exp_f32_e32 v58, v60
	v_exp_f32_e32 v59, v61
	s_waitcnt lgkmcnt(0)
	v_mfma_f32_32x32x16_bf16 v[40:55], v[224:227], v[80:83], v[40:55]
	ds_read_b128 v[224:227], v3 offset:4704
	v_add_f32_e64 v58, v58, 1.0
	v_add_f32_e64 v59, v59, 1.0
	v_exp_f32_e32 v60, v66
	v_rcp_f32_e32 v216, v58
	v_rcp_f32_e32 v217, v59
	v_exp_f32_e32 v58, v62
	v_exp_f32_e32 v59, v63
	s_waitcnt lgkmcnt(0)
	v_mfma_f32_32x32x16_bf16 v[40:55], v[224:227], v[76:79], v[40:55]
	v_add_f32_e64 v58, v58, 1.0
	v_add_f32_e64 v59, v59, 1.0
	v_exp_f32_e32 v61, v67
	v_rcp_f32_e32 v62, v58
	v_rcp_f32_e32 v63, v59
	v_exp_f32_e32 v58, v64
	v_exp_f32_e32 v59, v65
	v_exp_f32_e32 v64, v68
	s_nop 3
	v_exp_f32_e32 v44, v44
	v_exp_f32_e32 v45, v45
	v_exp_f32_e32 v65, v69
	v_exp_f32_e32 v66, v70
	v_exp_f32_e32 v67, v71
	v_pk_add_f32 v[44:45], v[44:45], 1.0 op_sel_hi:[1,0]
	v_exp_f32_e32 v40, v40
	v_rcp_f32_e32 v68, v44
	v_rcp_f32_e32 v69, v45
	v_exp_f32_e32 v44, v46
	v_exp_f32_e32 v45, v47
	v_exp_f32_e32 v41, v41
	v_exp_f32_e32 v42, v42
	v_exp_f32_e32 v43, v43
	v_pk_add_f32 v[44:45], v[44:45], 1.0 op_sel_hi:[1,0]
	v_exp_f32_e32 v46, v50
	v_rcp_f32_e32 v70, v44
	v_rcp_f32_e32 v71, v45
	v_exp_f32_e32 v44, v48
	v_exp_f32_e32 v45, v49
	v_exp_f32_e32 v47, v51
	v_exp_f32_e32 v48, v52
	v_exp_f32_e32 v49, v53
	v_exp_f32_e32 v50, v54
	v_exp_f32_e32 v51, v55
	v_pk_add_f32 v[4:5], v[4:5], 1.0 op_sel_hi:[1,0]
	v_pk_add_f32 v[58:59], v[58:59], 1.0 op_sel_hi:[1,0]
	v_pk_add_f32 v[60:61], v[60:61], 1.0 op_sel_hi:[1,0]
	v_pk_add_f32 v[64:65], v[64:65], 1.0 op_sel_hi:[1,0]
	v_pk_add_f32 v[66:67], v[66:67], 1.0 op_sel_hi:[1,0]
	v_pk_add_f32 v[40:41], v[40:41], 1.0 op_sel_hi:[1,0]
	v_pk_add_f32 v[42:43], v[42:43], 1.0 op_sel_hi:[1,0]
	v_pk_add_f32 v[44:45], v[44:45], 1.0 op_sel_hi:[1,0]
	v_pk_add_f32 v[46:47], v[46:47], 1.0 op_sel_hi:[1,0]
	v_pk_add_f32 v[48:49], v[48:49], 1.0 op_sel_hi:[1,0]
	v_pk_add_f32 v[50:51], v[50:51], 1.0 op_sel_hi:[1,0]
	v_rcp_f32_e32 v4, v4
	v_rcp_f32_e32 v5, v5
	v_rcp_f32_e32 v58, v58
	v_rcp_f32_e32 v59, v59
	v_rcp_f32_e32 v60, v60
	v_rcp_f32_e32 v61, v61
	v_rcp_f32_e32 v64, v64
	v_rcp_f32_e32 v65, v65
	v_rcp_f32_e32 v66, v66
	v_rcp_f32_e32 v67, v67
	v_rcp_f32_e32 v40, v40
	v_rcp_f32_e32 v41, v41
	v_rcp_f32_e32 v42, v42
	v_rcp_f32_e32 v43, v43
	v_rcp_f32_e32 v44, v44
	v_rcp_f32_e32 v45, v45
	v_rcp_f32_e32 v46, v46
	v_rcp_f32_e32 v47, v47
	v_rcp_f32_e32 v48, v48
	v_rcp_f32_e32 v49, v49
	v_rcp_f32_e32 v50, v50
	v_rcp_f32_e32 v51, v51
	s_cbranch_scc1 .LBB0_573
; DI void prompt_tile(const LAS unsigned char* kc, const LAS unsigned char* vc, const bf16x8 (&qf)[4], f32x16 (&accO)[2], float& carry, float bias2, int key0, int Q0, int r, int h2) {
;     ...
;         if (need_mask) {
;             asm volatile("" ::: "memory");
;             const int lim = Q0 + r - key0 - 4 * h2;
; #pragma unroll
;             for (int kb = 0; kb < 2; ++kb)
; #pragma unroll
;                 for (int pq = 0; pq < 8; ++pq) { const int ko = 32 * kb + ((2 * pq) & 3) + 8 * ((2 * pq) >> 2); if (ko >= lim) kp[kb][pq].x = 1.f; if (ko + 1 >= lim) kp[kb][pq].y = 1.f; }
;         }
	v_add_u32_e32 v3, s74, v191
	v_or_b32_e32 v39, s12, v206
	v_sub_u32_e32 v3, v3, v39
	v_cmp_lt_i32_e32 vcc, 0, v3
	v_cmp_lt_i32_e64 s[20:21], 1, v3
	s_or_b64 vcc, s[20:21], vcc
	v_cndmask_b32_e32 v56, 1.0, v56, vcc
	v_cndmask_b32_e64 v57, 1.0, v57, s[20:21]
	v_cmp_lt_i32_e32 vcc, 2, v3
	v_cmp_lt_i32_e64 s[20:21], 3, v3
	s_or_b64 vcc, s[20:21], vcc
	v_cndmask_b32_e32 v4, 1.0, v4, vcc
	v_cndmask_b32_e64 v5, 1.0, v5, s[20:21]
	v_cmp_lt_i32_e32 vcc, 8, v3
	v_cmp_lt_i32_e64 s[20:21], 9, v3
	s_or_b64 vcc, s[20:21], vcc
	v_cndmask_b32_e32 v216, 1.0, v216, vcc
	v_cndmask_b32_e64 v217, 1.0, v217, s[20:21]
	v_cmp_lt_i32_e32 vcc, 10, v3
	v_cmp_lt_i32_e64 s[20:21], 11, v3
	s_or_b64 vcc, s[20:21], vcc
	v_cndmask_b32_e32 v62, 1.0, v62, vcc
	v_cndmask_b32_e64 v63, 1.0, v63, s[20:21]
	v_cmp_lt_i32_e32 vcc, 16, v3
	v_cmp_lt_i32_e64 s[20:21], 17, v3
	s_or_b64 vcc, s[20:21], vcc
	v_cndmask_b32_e32 v58, 1.0, v58, vcc
	v_cndmask_b32_e64 v59, 1.0, v59, s[20:21]
	v_cmp_lt_i32_e32 vcc, 18, v3
	v_cmp_lt_i32_e64 s[20:21], 19, v3
	s_or_b64 vcc, s[20:21], vcc
	v_cndmask_b32_e32 v60, 1.0, v60, vcc
	v_cndmask_b32_e64 v61, 1.0, v61, s[20:21]
	v_cmp_lt_i32_e32 vcc, 24, v3
	v_cmp_lt_i32_e64 s[20:21], 25, v3
	s_or_b64 vcc, s[20:21], vcc
	v_cndmask_b32_e32 v64, 1.0, v64, vcc
	v_cndmask_b32_e64 v65, 1.0, v65, s[20:21]
	v_cmp_lt_i32_e32 vcc, 26, v3
	v_cmp_lt_i32_e64 s[20:21], 27, v3
	s_or_b64 vcc, s[20:21], vcc
	v_cndmask_b32_e32 v66, 1.0, v66, vcc
	v_cndmask_b32_e64 v67, 1.0, v67, s[20:21]
	v_cmp_lt_i32_e32 vcc, 32, v3
	v_cmp_lt_i32_e64 s[20:21], 33, v3
	s_or_b64 vcc, s[20:21], vcc
	v_cndmask_b32_e32 v40, 1.0, v40, vcc
	v_cndmask_b32_e64 v41, 1.0, v41, s[20:21]
	v_cmp_lt_i32_e32 vcc, 34, v3
	v_cmp_lt_i32_e64 s[20:21], 35, v3
	s_or_b64 vcc, s[20:21], vcc
	v_cndmask_b32_e32 v42, 1.0, v42, vcc
	v_cndmask_b32_e64 v43, 1.0, v43, s[20:21]
	v_cmp_lt_i32_e32 vcc, 40, v3
	v_cmp_lt_i32_e64 s[20:21], 41, v3
	s_or_b64 vcc, s[20:21], vcc
	v_cndmask_b32_e32 v68, 1.0, v68, vcc
	v_cndmask_b32_e64 v69, 1.0, v69, s[20:21]
	v_cmp_lt_i32_e32 vcc, 42, v3
	v_cmp_lt_i32_e64 s[20:21], 43, v3
	s_or_b64 vcc, s[20:21], vcc
	v_cndmask_b32_e32 v70, 1.0, v70, vcc
	v_cndmask_b32_e64 v71, 1.0, v71, s[20:21]
	v_cmp_lt_i32_e32 vcc, 48, v3
	v_cmp_lt_i32_e64 s[20:21], 49, v3
	s_or_b64 vcc, s[20:21], vcc
	v_cndmask_b32_e32 v44, 1.0, v44, vcc
	v_cndmask_b32_e64 v45, 1.0, v45, s[20:21]
	v_cmp_lt_i32_e32 vcc, 50, v3
	v_cmp_lt_i32_e64 s[20:21], 51, v3
	s_or_b64 vcc, s[20:21], vcc
	v_cndmask_b32_e32 v46, 1.0, v46, vcc
	v_cndmask_b32_e64 v47, 1.0, v47, s[20:21]
	v_cmp_lt_i32_e32 vcc, 56, v3
	v_cmp_lt_i32_e64 s[20:21], 57, v3
	s_or_b64 vcc, s[20:21], vcc
	v_cndmask_b32_e32 v48, 1.0, v48, vcc
	v_cndmask_b32_e64 v49, 1.0, v49, s[20:21]
	v_cmp_lt_i32_e32 vcc, 58, v3
	v_cmp_lt_i32_e64 s[20:21], 59, v3
	s_or_b64 vcc, s[20:21], vcc
	v_cndmask_b32_e32 v50, 1.0, v50, vcc
	v_cndmask_b32_e64 v51, 1.0, v51, s[20:21]
; #define LAS __attribute__((address_space(3)))
; DI unsigned pk2(float lo, float hi) { f32x2 v = {lo, hi}; return __builtin_bit_cast(unsigned, __builtin_convertvector(v, bf16v2)); }
; #define MFMA32(a, b, c) __builtin_amdgcn_mfma_f32_32x32x16_bf16((a), (b), (c), 0, 0, 0)
; DI void prompt_tile(const LAS unsigned char* kc, const LAS unsigned char* vc, const bf16x8 (&qf)[4], f32x16 (&accO)[2], float& carry, float bias2, int key0, int Q0, int r, int h2) {
;     ...
;         float R[2][4], Rp[2][4];
; #pragma unroll
;         for (int kb = 0; kb < 2; ++kb)
; #pragma unroll
;             for (int q = 0; q < 4; ++q) { const f32x2 pr = kp[kb][2 * q] * kp[kb][2 * q + 1]; R[kb][q] = pr.x * pr.y; Rp[kb][q] = __shfl_xor(R[kb][q], 32); }
;         float c = carry;
; #pragma unroll
;     ...
; #pragma unroll
;             for (int q = 3; q >= 0; --q) {
;                 const float E3 = c * (h2 ? 1.0f : Rp[kb][q]);
;                 c *= R[kb][q] * Rp[kb][q];
;                 const f32x2 ka = kp[kb][2 * q], kc = kp[kb][2 * q + 1];
;                 const float E2 = E3 * kc.y, E1 = E2 * kc.x, E0 = E1 * ka.y;
;                 const f32x2 w01 = (1.0f - ka) * (f32x2){E0, E1}, w23 = (1.0f - kc) * (f32x2){E2, E3};
;                 sk[kb][4 * q] = w01.x; sk[kb][4 * q + 1] = w01.y; sk[kb][4 * q + 2] = w23.x; sk[kb][4 * q + 3] = w23.y;
;             }
;         carry = c;
; #pragma unroll
;         for (int kb = 0; kb < 2; ++kb)
; #pragma unroll
;             for (int s = 0; s < 2; ++s) {
;                 u32x4 wp;
; #pragma unroll
;                 for (int j = 0; j < 4; ++j) wp[j] = pk2(sk[kb][8 * s + 2 * j], sk[kb][8 * s + 2 * j + 1]);
;                 const bf16x8 wf = __builtin_bit_cast(bf16x8, wp);
; #pragma unroll
;                 for (int db = 0; db < 2; ++db) {
;                     const LAS unsigned char* va = vc + (32 * db + r) * (VLD * 2) + (32 * kb + 16 * s + 4 * h2) * 2;
;                     const u32x2 lo = *(const LAS u32x2*)va, hi = *(const LAS u32x2*)(va + 16);
;                     const bf16x8 vf = __builtin_bit_cast(bf16x8, (u32x4){lo.x, lo.y, hi.x, hi.y});
;                     accO[db] = MFMA32(vf, wf, accO[db]);
;                 }
;             }
.LBB0_573:
	v_pk_mul_f32 v[52:53], v[216:217], v[62:63]
	v_pk_mul_f32 v[224:225], v[52:53], v[52:53] op_sel:[0,1] op_sel_hi:[1,0]
	v_pk_mul_f32 v[52:53], v[64:65], v[66:67]
	v_pk_mul_f32 v[228:229], v[52:53], v[52:53] op_sel:[0,1] op_sel_hi:[1,0]
	v_pk_mul_f32 v[52:53], v[48:49], v[50:51]
	v_pk_mul_f32 v[52:53], v[52:53], v[52:53] op_sel:[0,1] op_sel_hi:[1,0]
	ds_bpermute_b32 v53, v254, v52
	v_pk_mul_f32 v[234:235], v[44:45], v[46:47]
	v_readlane_b32 s14, v243, 43
	v_readlane_b32 s15, v243, 44
	v_mov_b32_e32 v240, v234
	v_mov_b32_e32 v241, v52
	v_mov_b32_e32 v52, v235
	v_pk_mul_f32 v[232:233], v[68:69], v[70:71]
	s_waitcnt lgkmcnt(0)
	v_cndmask_b32_e64 v39, 1.0, v53, s[14:15]
	v_pk_mul_f32 v[52:53], v[240:241], v[52:53]
	v_pk_mul_f32 v[232:233], v[232:233], v[232:233] op_sel:[0,1] op_sel_hi:[1,0]
	ds_bpermute_b32 v212, v254, v52
	ds_bpermute_b32 v233, v254, v232
	v_mul_f32_e32 v237, v213, v39
	v_pk_mul_f32 v[230:231], v[40:41], v[42:43]
	v_mul_f32_e32 v236, v51, v237
	s_waitcnt lgkmcnt(1)
	v_pk_mul_f32 v[52:53], v[52:53], v[212:213]
	v_mul_f32_e32 v239, v50, v236
	v_pk_add_f32 v[50:51], v[50:51], 1.0 op_sel_hi:[1,0] neg_lo:[1,0] neg_hi:[1,0]
	v_pk_mul_f32 v[234:235], v[52:53], v[52:53] op_sel:[0,1] op_sel_hi:[1,0]
	s_waitcnt lgkmcnt(0)
	v_cndmask_b32_e64 v39, 1.0, v233, s[14:15]
	v_mov_b32_e32 v240, v230
	v_mov_b32_e32 v241, v232
	v_mov_b32_e32 v232, v231
	v_pk_mul_f32 v[50:51], v[50:51], v[236:237]
	v_mul_f32_e32 v237, v39, v234
	v_pk_mul_f32 v[230:231], v[240:241], v[232:233]
	ds_bpermute_b32 v229, v254, v228
	v_mul_f32_e32 v238, v49, v239
	v_pk_add_f32 v[48:49], v[48:49], 1.0 op_sel_hi:[1,0] neg_lo:[1,0] neg_hi:[1,0]
	v_mul_f32_e32 v236, v71, v237
	ds_bpermute_b32 v232, v254, v230
	v_pk_mul_f32 v[48:49], v[48:49], v[238:239]
	v_mul_f32_e32 v239, v70, v236
	v_mul_f32_e32 v238, v69, v239
	v_pk_add_f32 v[68:69], v[68:69], 1.0 op_sel_hi:[1,0] neg_lo:[1,0] neg_hi:[1,0]
	v_pk_mul_f32 v[226:227], v[58:59], v[60:61]
	v_pk_mul_f32 v[238:239], v[68:69], v[238:239]
	v_pk_add_f32 v[68:69], v[70:71], 1.0 op_sel_hi:[1,0] neg_lo:[1,0] neg_hi:[1,0]
	v_mov_b32_e32 v233, v234
	v_pk_mul_f32 v[70:71], v[68:69], v[236:237]
	v_mov_b32_e32 v236, v226
	v_mov_b32_e32 v237, v228
	v_mov_b32_e32 v228, v227
	s_waitcnt lgkmcnt(0)
	v_pk_mul_f32 v[230:231], v[230:231], v[232:233]
	v_pk_mul_f32 v[226:227], v[236:237], v[228:229]
	v_pk_mul_f32 v[68:69], v[230:231], v[230:231] op_sel:[0,1] op_sel_hi:[1,0]
	v_cndmask_b32_e64 v52, 1.0, v229, s[14:15]
	ds_bpermute_b32 v228, v254, v226
	ds_bpermute_b32 v225, v254, v224
	v_mul_f32_e32 v233, v52, v68
	v_cndmask_b32_e64 v39, 1.0, v232, s[14:15]
	v_mul_f32_e32 v232, v67, v233
	v_mul_f32_e32 v235, v66, v232
	v_pk_mul_f32 v[54:55], v[56:57], v[4:5]
	v_mul_f32_e32 v234, v65, v235
	v_pk_add_f32 v[64:65], v[64:65], 1.0 op_sel_hi:[1,0] neg_lo:[1,0] neg_hi:[1,0]
	v_mov_b32_e32 v229, v68
	v_pk_mul_f32 v[234:235], v[64:65], v[234:235]
	v_pk_add_f32 v[64:65], v[66:67], 1.0 op_sel_hi:[1,0] neg_lo:[1,0] neg_hi:[1,0]
	s_waitcnt lgkmcnt(1)
	v_cndmask_b32_e64 v52, 1.0, v228, s[14:15]
	v_pk_mul_f32 v[226:227], v[226:227], v[228:229]
	v_mov_b32_e32 v228, v54
	v_mov_b32_e32 v229, v224
	v_mov_b32_e32 v224, v55
	v_pk_mul_f32 v[232:233], v[64:65], v[232:233]
	v_pk_mul_f32 v[64:65], v[226:227], v[226:227] op_sel:[0,1] op_sel_hi:[1,0]
	s_waitcnt lgkmcnt(0)
	v_pk_mul_f32 v[54:55], v[228:229], v[224:225]
	v_cndmask_b32_e64 v65, 1.0, v225, s[14:15]
	ds_bpermute_b32 v224, v254, v54
	v_mul_f32_e32 v67, v65, v64
	v_mul_f32_e32 v66, v63, v67
	v_mul_f32_e32 v69, v62, v66
	v_mul_f32_e32 v68, v217, v69
	v_pk_add_f32 v[216:217], v[216:217], 1.0 op_sel_hi:[1,0] neg_lo:[1,0] neg_hi:[1,0]
	v_mov_b32_e32 v225, v64
	v_pk_mul_f32 v[68:69], v[216:217], v[68:69]
	v_pk_add_f32 v[62:63], v[62:63], 1.0 op_sel_hi:[1,0] neg_lo:[1,0] neg_hi:[1,0]
	s_waitcnt lgkmcnt(0)
	v_cndmask_b32_e64 v3, 1.0, v224, s[14:15]
	v_pk_mul_f32 v[216:217], v[54:55], v[224:225]
	v_pk_mul_f32 v[66:67], v[62:63], v[66:67]
	v_mul_f32_e32 v63, v3, v217
	s_mul_i32 s12, s2, 0x2200
	v_mul_f32_e32 v62, v5, v63
	v_mul_f32_e32 v55, v4, v62
	v_add3_u32 v3, v220, s12, v221
	v_mul_f32_e32 v54, v57, v55
	v_pk_add_f32 v[56:57], v[56:57], 1.0 op_sel_hi:[1,0] neg_lo:[1,0] neg_hi:[1,0]
	v_add_u32_e32 v213, 0x4800, v3
	v_pk_mul_f32 v[64:65], v[56:57], v[54:55]
	ds_read2_b64 v[54:57], v213 offset1:2
	v_pk_add_f32 v[4:5], v[4:5], 1.0 op_sel_hi:[1,0] neg_lo:[1,0] neg_hi:[1,0]
	v_add_u32_e32 v3, 0x5800, v3
	v_pk_mul_f32 v[4:5], v[4:5], v[62:63]
	v_cvt_pk_bf16_f32 v62, v64, v65
	v_cvt_pk_bf16_f32 v64, v68, v69
	v_cvt_pk_bf16_f32 v65, v66, v67
	ds_read2_b64 v[66:69], v3 offset0:32 offset1:34
	v_cvt_pk_bf16_f32 v63, v4, v5
	v_mul_f32_e32 v5, v52, v227
	v_mul_f32_e32 v4, v61, v5
	s_waitcnt lgkmcnt(1)
	v_mfma_f32_32x32x16_bf16 v[6:21], v[54:57], v[62:65], v[6:21]
	v_mul_f32_e32 v55, v60, v4
	v_mul_f32_e32 v54, v59, v55
	v_add_f32_e64 v56, -v58, 1.0
	v_add_f32_e64 v57, -v59, 1.0
	v_add_f32_e64 v60, -v60, 1.0
	v_add_f32_e64 v61, -v61, 1.0
	v_pk_mul_f32 v[58:59], v[56:57], v[54:55]
	ds_read2_b64 v[54:57], v213 offset0:4 offset1:6
	v_pk_mul_f32 v[4:5], v[60:61], v[4:5]
	s_waitcnt lgkmcnt(1)
	v_mfma_f32_32x32x16_bf16 v[22:37], v[66:69], v[62:65], v[22:37]
	ds_read2_b64 v[62:65], v3 offset0:36 offset1:38
	v_cvt_pk_bf16_f32 v58, v58, v59
	v_cvt_pk_bf16_f32 v59, v4, v5
	v_mul_f32_e32 v5, v39, v231
	v_cvt_pk_bf16_f32 v60, v234, v235
	v_cvt_pk_bf16_f32 v61, v232, v233
	v_mul_f32_e32 v4, v43, v5
	s_waitcnt lgkmcnt(1)
	v_mfma_f32_32x32x16_bf16 v[6:21], v[54:57], v[58:61], v[6:21]
	v_mul_f32_e32 v55, v42, v4
	v_mul_f32_e32 v54, v41, v55
	v_add_f32_e64 v40, -v40, 1.0
	v_add_f32_e64 v41, -v41, 1.0
	v_add_f32_e64 v42, -v42, 1.0
	v_add_f32_e64 v43, -v43, 1.0
	v_pk_mul_f32 v[40:41], v[40:41], v[54:55]
	ds_read2_b64 v[54:57], v213 offset0:8 offset1:10
	v_pk_mul_f32 v[4:5], v[42:43], v[4:5]
	s_waitcnt lgkmcnt(1)
	v_mfma_f32_32x32x16_bf16 v[22:37], v[62:65], v[58:61], v[22:37]
	ds_read2_b64 v[58:61], v3 offset0:40 offset1:42
	v_cvt_pk_bf16_f32 v40, v40, v41
	v_cvt_pk_bf16_f32 v41, v4, v5
	v_cndmask_b32_e64 v4, 1.0, v212, s[14:15]
	v_mul_f32_e32 v5, v4, v53
	v_cvt_pk_bf16_f32 v42, v238, v239
	v_cvt_pk_bf16_f32 v43, v70, v71
	v_mul_f32_e32 v4, v47, v5
	s_waitcnt lgkmcnt(1)
	v_mfma_f32_32x32x16_bf16 v[6:21], v[54:57], v[40:43], v[6:21]
	v_mul_f32_e32 v57, v46, v4
	v_mul_f32_e32 v56, v45, v57
	v_add_f32_e64 v44, -v44, 1.0
	v_add_f32_e64 v45, -v45, 1.0
	ds_read2_b64 v[52:55], v213 offset0:12 offset1:14
	v_mul_f32_e32 v213, v216, v217
	s_waitcnt lgkmcnt(1)
	v_mfma_f32_32x32x16_bf16 v[22:37], v[58:61], v[40:43], v[22:37]
	v_mul_f32_e64 v40, v44, v56
	v_mul_f32_e64 v41, v45, v57
	v_add_f32_e64 v42, -v46, 1.0
	v_add_f32_e64 v43, -v47, 1.0
	ds_read2_b64 v[44:47], v3 offset0:44 offset1:46
	v_pk_mul_f32 v[4:5], v[42:43], v[4:5]
	v_cvt_pk_bf16_f32 v40, v40, v41
	v_cvt_pk_bf16_f32 v41, v4, v5
	v_cvt_pk_bf16_f32 v42, v48, v49
	v_cvt_pk_bf16_f32 v43, v50, v51
	s_waitcnt lgkmcnt(1)
	s_nop 0
	v_mfma_f32_32x32x16_bf16 v[6:21], v[52:55], v[40:43], v[6:21]
	s_waitcnt lgkmcnt(0)
	v_mfma_f32_32x32x16_bf16 v[22:37], v[44:47], v[40:43], v[22:37]

; #define LAS __attribute__((address_space(3)))
; DI float fexp2(float x) { return __builtin_amdgcn_exp2f(x); }
; DI float frcp(float x) { return __builtin_amdgcn_rcpf(x); }
; #define MFMA32(a, b, c) __builtin_amdgcn_mfma_f32_32x32x16_bf16((a), (b), (c), 0, 0, 0)
; DI void prompt_tile(const LAS unsigned char* kc, const LAS unsigned char* vc, const bf16x8 (&qf)[4], f32x16 (&accO)[2], float& carry, float bias2, int key0, int Q0, int r, int h2) {
;     ...
;     if (key0 < Q0 + 31) {
;         f32x16 sk[2];
; #pragma unroll
;         for (int kb = 0; kb < 2; ++kb) {
; #pragma unroll
;             for (int i = 0; i < 16; ++i) sk[kb][i] = bias2;
; #pragma unroll
;             for (int s = 0; s < 4; ++s) { const bf16x8 a = *(const LAS bf16x8*)(kc + (32 * kb + r) * (KLD * 2) + (16 * s + 8 * h2) * 2); sk[kb] = MFMA32(a, qf[s], sk[kb]); }
;         }
;         const bool need_mask = key0 + 63 >= Q0;
;         f32x2 kp[2][8];
; #pragma unroll
;         for (int kb = 0; kb < 2; ++kb)
; #pragma unroll
;             for (int pq = 0; pq < 8; ++pq) {
;                 f32x2 e2; e2.x = fexp2(sk[kb][2 * pq]); e2.y = fexp2(sk[kb][2 * pq + 1]);
;                 const f32x2 d2 = e2 + 1.0f;
;                 f32x2 k2; k2.x = frcp(d2.x); k2.y = frcp(d2.y);
;                 kp[kb][pq] = k2;
;             }
.LBB0_633:
	s_max_i32 s16, s75, 2
	s_lshl_b32 s16, s16, 6
	s_addk_i32 s16, 0xff80
	s_ashr_i32 s17, s16, 31
	s_lshl_b64 s[18:19], s[16:17], 10
	v_lshl_add_u64 v[4:5], v[208:209], 0, s[18:19]
	global_load_dwordx4 v[168:171], v[4:5], off
	v_lshl_add_u64 v[4:5], s[16:17], 1, v[210:211]
	global_load_dwordx4 v[172:175], v[4:5], off
	v_cndmask_b32_e64 v3, 0, 1, s[12:13]
	v_cmp_ne_u32_e64 s[18:19], 1, v3
	s_andn2_b64 vcc, exec, s[12:13]
	s_cbranch_vccnz .LBB0_646
	s_lshl_b32 s12, s75, 6
	s_add_i32 s13, s74, 31
	v_readlane_b32 s16, v243, 24
	s_cmp_ge_i32 s12, s13
	v_readlane_b32 s17, v243, 25
	s_cbranch_scc1 .LBB0_638
	s_mul_i32 s13, s2, 0x2400
	v_add3_u32 v3, v218, s13, v219
	ds_read_b128 v[224:227], v3
	ds_read_b128 v[228:231], v3 offset:32
	v_mov_b32_e32 v39, v38
	v_mov_b64_e32 v[40:41], v[38:39]
	v_mov_b64_e32 v[42:43], v[38:39]
	v_mov_b64_e32 v[44:45], v[38:39]
	v_mov_b64_e32 v[46:47], v[38:39]
	v_mov_b64_e32 v[48:49], v[38:39]
	v_mov_b64_e32 v[50:51], v[38:39]
	v_mov_b64_e32 v[52:53], v[38:39]
	s_or_b32 s13, s12, 63
	s_cmp_lt_i32 s13, s74
	s_waitcnt lgkmcnt(1)
	v_mfma_f32_32x32x16_bf16 v[56:71], v[224:227], v[72:75], v[38:53]
	ds_read_b128 v[224:227], v3 offset:64
	v_mov_b64_e32 v[54:55], v[52:53]
	s_waitcnt lgkmcnt(1)
	v_mfma_f32_32x32x16_bf16 v[56:71], v[228:231], v[84:87], v[56:71]
	s_waitcnt lgkmcnt(0)
	v_mfma_f32_32x32x16_bf16 v[56:71], v[224:227], v[80:83], v[56:71]
	ds_read_b128 v[224:227], v3 offset:96
	s_waitcnt lgkmcnt(0)
	v_mfma_f32_32x32x16_bf16 v[56:71], v[224:227], v[76:79], v[56:71]
	ds_read_b128 v[224:227], v3 offset:4608
	s_waitcnt lgkmcnt(0)
	v_mfma_f32_32x32x16_bf16 v[40:55], v[224:227], v[72:75], v[40:55]
	ds_read_b128 v[224:227], v3 offset:4640
	s_nop 7
	v_exp_f32_e32 v4, v56
	v_exp_f32_e32 v5, v57
	s_nop 0
	v_pk_add_f32 v[4:5], v[4:5], 1.0 op_sel_hi:[1,0]
	s_waitcnt lgkmcnt(0)
	v_mfma_f32_32x32x16_bf16 v[40:55], v[224:227], v[84:87], v[40:55]
	ds_read_b128 v[224:227], v3 offset:4672
	v_rcp_f32_e32 v56, v4
	v_rcp_f32_e32 v57, v5
	v_exp_f32_e32 v4, v58
	v_exp_f32_e32 v5, v59
	v_exp_f32_e32 v58, v60
	v_exp_f32_e32 v59, v61
	s_waitcnt lgkmcnt(0)
	v_mfma_f32_32x32x16_bf16 v[40:55], v[224:227], v[80:83], v[40:55]
	ds_read_b128 v[224:227], v3 offset:4704
	v_add_f32_e64 v58, v58, 1.0
	v_add_f32_e64 v59, v59, 1.0
	v_exp_f32_e32 v60, v66
	v_rcp_f32_e32 v216, v58
	v_rcp_f32_e32 v217, v59
	v_exp_f32_e32 v58, v62
	v_exp_f32_e32 v59, v63
	s_waitcnt lgkmcnt(0)
	v_mfma_f32_32x32x16_bf16 v[40:55], v[224:227], v[76:79], v[40:55]
	v_add_f32_e64 v58, v58, 1.0
	v_add_f32_e64 v59, v59, 1.0
	v_exp_f32_e32 v61, v67
	v_rcp_f32_e32 v62, v58
	v_rcp_f32_e32 v63, v59
	v_exp_f32_e32 v58, v64
	v_exp_f32_e32 v59, v65
	v_exp_f32_e32 v64, v68
	s_nop 3
	v_exp_f32_e32 v44, v44
	v_exp_f32_e32 v45, v45
	v_exp_f32_e32 v65, v69
	v_exp_f32_e32 v66, v70
	v_exp_f32_e32 v67, v71
	v_pk_add_f32 v[44:45], v[44:45], 1.0 op_sel_hi:[1,0]
	v_exp_f32_e32 v40, v40
	v_rcp_f32_e32 v68, v44
	v_rcp_f32_e32 v69, v45
	v_exp_f32_e32 v44, v46
	v_exp_f32_e32 v45, v47
	v_exp_f32_e32 v41, v41
	v_exp_f32_e32 v42, v42
	v_exp_f32_e32 v43, v43
	v_pk_add_f32 v[44:45], v[44:45], 1.0 op_sel_hi:[1,0]
	v_exp_f32_e32 v46, v50
	v_rcp_f32_e32 v70, v44
	v_rcp_f32_e32 v71, v45
	v_exp_f32_e32 v44, v48
	v_exp_f32_e32 v45, v49
	v_exp_f32_e32 v47, v51
	v_exp_f32_e32 v48, v52
	v_exp_f32_e32 v49, v53
	v_exp_f32_e32 v50, v54
	v_exp_f32_e32 v51, v55
	v_pk_add_f32 v[4:5], v[4:5], 1.0 op_sel_hi:[1,0]
	v_pk_add_f32 v[58:59], v[58:59], 1.0 op_sel_hi:[1,0]
	v_pk_add_f32 v[60:61], v[60:61], 1.0 op_sel_hi:[1,0]
	v_pk_add_f32 v[64:65], v[64:65], 1.0 op_sel_hi:[1,0]
	v_pk_add_f32 v[66:67], v[66:67], 1.0 op_sel_hi:[1,0]
	v_pk_add_f32 v[40:41], v[40:41], 1.0 op_sel_hi:[1,0]
	v_pk_add_f32 v[42:43], v[42:43], 1.0 op_sel_hi:[1,0]
	v_pk_add_f32 v[44:45], v[44:45], 1.0 op_sel_hi:[1,0]
	v_pk_add_f32 v[46:47], v[46:47], 1.0 op_sel_hi:[1,0]
	v_pk_add_f32 v[48:49], v[48:49], 1.0 op_sel_hi:[1,0]
	v_pk_add_f32 v[50:51], v[50:51], 1.0 op_sel_hi:[1,0]
	v_rcp_f32_e32 v4, v4
	v_rcp_f32_e32 v5, v5
	v_rcp_f32_e32 v58, v58
	v_rcp_f32_e32 v59, v59
	v_rcp_f32_e32 v60, v60
	v_rcp_f32_e32 v61, v61
	v_rcp_f32_e32 v64, v64
	v_rcp_f32_e32 v65, v65
	v_rcp_f32_e32 v66, v66
	v_rcp_f32_e32 v67, v67
	v_rcp_f32_e32 v40, v40
	v_rcp_f32_e32 v41, v41
	v_rcp_f32_e32 v42, v42
	v_rcp_f32_e32 v43, v43
	v_rcp_f32_e32 v44, v44
	v_rcp_f32_e32 v45, v45
	v_rcp_f32_e32 v46, v46
	v_rcp_f32_e32 v47, v47
	v_rcp_f32_e32 v48, v48
	v_rcp_f32_e32 v49, v49
	v_rcp_f32_e32 v50, v50
	v_rcp_f32_e32 v51, v51
	s_cbranch_scc1 .LBB0_637
; DI void prompt_tile(const LAS unsigned char* kc, const LAS unsigned char* vc, const bf16x8 (&qf)[4], f32x16 (&accO)[2], float& carry, float bias2, int key0, int Q0, int r, int h2) {
;     ...
;         if (need_mask) {
;             asm volatile("" ::: "memory");
;             const int lim = Q0 + r - key0 - 4 * h2;
; #pragma unroll
;             for (int kb = 0; kb < 2; ++kb)
; #pragma unroll
;                 for (int pq = 0; pq < 8; ++pq) { const int ko = 32 * kb + ((2 * pq) & 3) + 8 * ((2 * pq) >> 2); if (ko >= lim) kp[kb][pq].x = 1.f; if (ko + 1 >= lim) kp[kb][pq].y = 1.f; }
;         }
	v_add_u32_e32 v3, s74, v191
	v_or_b32_e32 v39, s12, v206
	v_sub_u32_e32 v3, v3, v39
	v_cmp_lt_i32_e32 vcc, 0, v3
	v_cmp_lt_i32_e64 s[20:21], 1, v3
	s_or_b64 vcc, s[20:21], vcc
	v_cndmask_b32_e32 v56, 1.0, v56, vcc
	v_cndmask_b32_e64 v57, 1.0, v57, s[20:21]
	v_cmp_lt_i32_e32 vcc, 2, v3
	v_cmp_lt_i32_e64 s[20:21], 3, v3
	s_or_b64 vcc, s[20:21], vcc
	v_cndmask_b32_e32 v4, 1.0, v4, vcc
	v_cndmask_b32_e64 v5, 1.0, v5, s[20:21]
	v_cmp_lt_i32_e32 vcc, 8, v3
	v_cmp_lt_i32_e64 s[20:21], 9, v3
	s_or_b64 vcc, s[20:21], vcc
	v_cndmask_b32_e32 v216, 1.0, v216, vcc
	v_cndmask_b32_e64 v217, 1.0, v217, s[20:21]
	v_cmp_lt_i32_e32 vcc, 10, v3
	v_cmp_lt_i32_e64 s[20:21], 11, v3
	s_or_b64 vcc, s[20:21], vcc
	v_cndmask_b32_e32 v62, 1.0, v62, vcc
	v_cndmask_b32_e64 v63, 1.0, v63, s[20:21]
	v_cmp_lt_i32_e32 vcc, 16, v3
	v_cmp_lt_i32_e64 s[20:21], 17, v3
	s_or_b64 vcc, s[20:21], vcc
	v_cndmask_b32_e32 v58, 1.0, v58, vcc
	v_cndmask_b32_e64 v59, 1.0, v59, s[20:21]
	v_cmp_lt_i32_e32 vcc, 18, v3
	v_cmp_lt_i32_e64 s[20:21], 19, v3
	s_or_b64 vcc, s[20:21], vcc
	v_cndmask_b32_e32 v60, 1.0, v60, vcc
	v_cndmask_b32_e64 v61, 1.0, v61, s[20:21]
	v_cmp_lt_i32_e32 vcc, 24, v3
	v_cmp_lt_i32_e64 s[20:21], 25, v3
	s_or_b64 vcc, s[20:21], vcc
	v_cndmask_b32_e32 v64, 1.0, v64, vcc
	v_cndmask_b32_e64 v65, 1.0, v65, s[20:21]
	v_cmp_lt_i32_e32 vcc, 26, v3
	v_cmp_lt_i32_e64 s[20:21], 27, v3
	s_or_b64 vcc, s[20:21], vcc
	v_cndmask_b32_e32 v66, 1.0, v66, vcc
	v_cndmask_b32_e64 v67, 1.0, v67, s[20:21]
	v_cmp_lt_i32_e32 vcc, 32, v3
	v_cmp_lt_i32_e64 s[20:21], 33, v3
	s_or_b64 vcc, s[20:21], vcc
	v_cndmask_b32_e32 v40, 1.0, v40, vcc
	v_cndmask_b32_e64 v41, 1.0, v41, s[20:21]
	v_cmp_lt_i32_e32 vcc, 34, v3
	v_cmp_lt_i32_e64 s[20:21], 35, v3
	s_or_b64 vcc, s[20:21], vcc
	v_cndmask_b32_e32 v42, 1.0, v42, vcc
	v_cndmask_b32_e64 v43, 1.0, v43, s[20:21]
	v_cmp_lt_i32_e32 vcc, 40, v3
	v_cmp_lt_i32_e64 s[20:21], 41, v3
	s_or_b64 vcc, s[20:21], vcc
	v_cndmask_b32_e32 v68, 1.0, v68, vcc
	v_cndmask_b32_e64 v69, 1.0, v69, s[20:21]
	v_cmp_lt_i32_e32 vcc, 42, v3
	v_cmp_lt_i32_e64 s[20:21], 43, v3
	s_or_b64 vcc, s[20:21], vcc
	v_cndmask_b32_e32 v70, 1.0, v70, vcc
	v_cndmask_b32_e64 v71, 1.0, v71, s[20:21]
	v_cmp_lt_i32_e32 vcc, 48, v3
	v_cmp_lt_i32_e64 s[20:21], 49, v3
	s_or_b64 vcc, s[20:21], vcc
	v_cndmask_b32_e32 v44, 1.0, v44, vcc
	v_cndmask_b32_e64 v45, 1.0, v45, s[20:21]
	v_cmp_lt_i32_e32 vcc, 50, v3
	v_cmp_lt_i32_e64 s[20:21], 51, v3
	s_or_b64 vcc, s[20:21], vcc
	v_cndmask_b32_e32 v46, 1.0, v46, vcc
	v_cndmask_b32_e64 v47, 1.0, v47, s[20:21]
	v_cmp_lt_i32_e32 vcc, 56, v3
	v_cmp_lt_i32_e64 s[20:21], 57, v3
	s_or_b64 vcc, s[20:21], vcc
	v_cndmask_b32_e32 v48, 1.0, v48, vcc
	v_cndmask_b32_e64 v49, 1.0, v49, s[20:21]
	v_cmp_lt_i32_e32 vcc, 58, v3
	v_cmp_lt_i32_e64 s[20:21], 59, v3
	s_or_b64 vcc, s[20:21], vcc
	v_cndmask_b32_e32 v50, 1.0, v50, vcc
	v_cndmask_b32_e64 v51, 1.0, v51, s[20:21]
; #define LAS __attribute__((address_space(3)))
; DI unsigned pk2(float lo, float hi) { f32x2 v = {lo, hi}; return __builtin_bit_cast(unsigned, __builtin_convertvector(v, bf16v2)); }
; #define MFMA32(a, b, c) __builtin_amdgcn_mfma_f32_32x32x16_bf16((a), (b), (c), 0, 0, 0)
; DI void prompt_tile(const LAS unsigned char* kc, const LAS unsigned char* vc, const bf16x8 (&qf)[4], f32x16 (&accO)[2], float& carry, float bias2, int key0, int Q0, int r, int h2) {
;     ...
;         float R[2][4], Rp[2][4];
; #pragma unroll
;         for (int kb = 0; kb < 2; ++kb)
; #pragma unroll
;             for (int q = 0; q < 4; ++q) { const f32x2 pr = kp[kb][2 * q] * kp[kb][2 * q + 1]; R[kb][q] = pr.x * pr.y; Rp[kb][q] = __shfl_xor(R[kb][q], 32); }
;         float c = carry;
; #pragma unroll
;     ...
; #pragma unroll
;             for (int q = 3; q >= 0; --q) {
;                 const float E3 = c * (h2 ? 1.0f : Rp[kb][q]);
;                 c *= R[kb][q] * Rp[kb][q];
;                 const f32x2 ka = kp[kb][2 * q], kc = kp[kb][2 * q + 1];
;                 const float E2 = E3 * kc.y, E1 = E2 * kc.x, E0 = E1 * ka.y;
;                 const f32x2 w01 = (1.0f - ka) * (f32x2){E0, E1}, w23 = (1.0f - kc) * (f32x2){E2, E3};
;                 sk[kb][4 * q] = w01.x; sk[kb][4 * q + 1] = w01.y; sk[kb][4 * q + 2] = w23.x; sk[kb][4 * q + 3] = w23.y;
;             }
;         carry = c;
; #pragma unroll
;         for (int kb = 0; kb < 2; ++kb)
; #pragma unroll
;             for (int s = 0; s < 2; ++s) {
;                 u32x4 wp;
; #pragma unroll
;                 for (int j = 0; j < 4; ++j) wp[j] = pk2(sk[kb][8 * s + 2 * j], sk[kb][8 * s + 2 * j + 1]);
;                 const bf16x8 wf = __builtin_bit_cast(bf16x8, wp);
; #pragma unroll
;                 for (int db = 0; db < 2; ++db) {
;                     const LAS unsigned char* va = vc + (32 * db + r) * (VLD * 2) + (32 * kb + 16 * s + 4 * h2) * 2;
;                     const u32x2 lo = *(const LAS u32x2*)va, hi = *(const LAS u32x2*)(va + 16);
;                     const bf16x8 vf = __builtin_bit_cast(bf16x8, (u32x4){lo.x, lo.y, hi.x, hi.y});
;                     accO[db] = MFMA32(vf, wf, accO[db]);
;                 }
;             }
.LBB0_637:
	v_pk_mul_f32 v[52:53], v[216:217], v[62:63]
	v_pk_mul_f32 v[224:225], v[52:53], v[52:53] op_sel:[0,1] op_sel_hi:[1,0]
	v_pk_mul_f32 v[52:53], v[64:65], v[66:67]
	v_pk_mul_f32 v[228:229], v[52:53], v[52:53] op_sel:[0,1] op_sel_hi:[1,0]
	v_pk_mul_f32 v[52:53], v[48:49], v[50:51]
	v_pk_mul_f32 v[52:53], v[52:53], v[52:53] op_sel:[0,1] op_sel_hi:[1,0]
	ds_bpermute_b32 v53, v254, v52
	v_pk_mul_f32 v[234:235], v[44:45], v[46:47]
	v_readlane_b32 s6, v243, 43
	v_readlane_b32 s7, v243, 44
	v_mov_b32_e32 v240, v234
	v_mov_b32_e32 v241, v52
	v_mov_b32_e32 v52, v235
	v_pk_mul_f32 v[232:233], v[68:69], v[70:71]
	s_waitcnt lgkmcnt(0)
	v_cndmask_b32_e64 v39, 1.0, v53, s[6:7]
	v_pk_mul_f32 v[52:53], v[240:241], v[52:53]
	v_pk_mul_f32 v[232:233], v[232:233], v[232:233] op_sel:[0,1] op_sel_hi:[1,0]
	ds_bpermute_b32 v212, v254, v52
	ds_bpermute_b32 v233, v254, v232
	v_mul_f32_e32 v237, v213, v39
	v_pk_mul_f32 v[230:231], v[40:41], v[42:43]
	v_mul_f32_e32 v236, v51, v237
	s_waitcnt lgkmcnt(1)
	v_pk_mul_f32 v[52:53], v[52:53], v[212:213]
	v_mul_f32_e32 v239, v50, v236
	v_pk_add_f32 v[50:51], v[50:51], 1.0 op_sel_hi:[1,0] neg_lo:[1,0] neg_hi:[1,0]
	v_pk_mul_f32 v[234:235], v[52:53], v[52:53] op_sel:[0,1] op_sel_hi:[1,0]
	s_waitcnt lgkmcnt(0)
	v_cndmask_b32_e64 v39, 1.0, v233, s[6:7]
	v_mov_b32_e32 v240, v230
	v_mov_b32_e32 v241, v232
	v_mov_b32_e32 v232, v231
	v_pk_mul_f32 v[50:51], v[50:51], v[236:237]
	v_mul_f32_e32 v237, v39, v234
	v_pk_mul_f32 v[230:231], v[240:241], v[232:233]
	ds_bpermute_b32 v229, v254, v228
	v_mul_f32_e32 v238, v49, v239
	v_pk_add_f32 v[48:49], v[48:49], 1.0 op_sel_hi:[1,0] neg_lo:[1,0] neg_hi:[1,0]
	v_mul_f32_e32 v236, v71, v237
	ds_bpermute_b32 v232, v254, v230
	v_pk_mul_f32 v[48:49], v[48:49], v[238:239]
	v_mul_f32_e32 v239, v70, v236
	v_mul_f32_e32 v238, v69, v239
	v_pk_add_f32 v[68:69], v[68:69], 1.0 op_sel_hi:[1,0] neg_lo:[1,0] neg_hi:[1,0]
	v_pk_mul_f32 v[226:227], v[58:59], v[60:61]
	v_pk_mul_f32 v[238:239], v[68:69], v[238:239]
	v_pk_add_f32 v[68:69], v[70:71], 1.0 op_sel_hi:[1,0] neg_lo:[1,0] neg_hi:[1,0]
	v_mov_b32_e32 v233, v234
	v_pk_mul_f32 v[70:71], v[68:69], v[236:237]
	v_mov_b32_e32 v236, v226
	v_mov_b32_e32 v237, v228
	v_mov_b32_e32 v228, v227
	s_waitcnt lgkmcnt(0)
	v_pk_mul_f32 v[230:231], v[230:231], v[232:233]
	v_pk_mul_f32 v[226:227], v[236:237], v[228:229]
	v_pk_mul_f32 v[68:69], v[230:231], v[230:231] op_sel:[0,1] op_sel_hi:[1,0]
	v_cndmask_b32_e64 v52, 1.0, v229, s[6:7]
	ds_bpermute_b32 v228, v254, v226
	ds_bpermute_b32 v225, v254, v224
	v_mul_f32_e32 v233, v52, v68
	v_cndmask_b32_e64 v39, 1.0, v232, s[6:7]
	v_mul_f32_e32 v232, v67, v233
	v_mul_f32_e32 v235, v66, v232
	v_pk_mul_f32 v[54:55], v[56:57], v[4:5]
	v_mul_f32_e32 v234, v65, v235
	v_pk_add_f32 v[64:65], v[64:65], 1.0 op_sel_hi:[1,0] neg_lo:[1,0] neg_hi:[1,0]
	v_mov_b32_e32 v229, v68
	v_pk_mul_f32 v[234:235], v[64:65], v[234:235]
	v_pk_add_f32 v[64:65], v[66:67], 1.0 op_sel_hi:[1,0] neg_lo:[1,0] neg_hi:[1,0]
	s_waitcnt lgkmcnt(1)
	v_cndmask_b32_e64 v52, 1.0, v228, s[6:7]
	v_pk_mul_f32 v[226:227], v[226:227], v[228:229]
	v_mov_b32_e32 v228, v54
	v_mov_b32_e32 v229, v224
	v_mov_b32_e32 v224, v55
	v_pk_mul_f32 v[232:233], v[64:65], v[232:233]
	v_pk_mul_f32 v[64:65], v[226:227], v[226:227] op_sel:[0,1] op_sel_hi:[1,0]
	s_waitcnt lgkmcnt(0)
	v_pk_mul_f32 v[54:55], v[228:229], v[224:225]
	v_cndmask_b32_e64 v65, 1.0, v225, s[6:7]
	ds_bpermute_b32 v224, v254, v54
	v_mul_f32_e32 v67, v65, v64
	v_mul_f32_e32 v66, v63, v67
	v_mul_f32_e32 v69, v62, v66
	v_mul_f32_e32 v68, v217, v69
	v_pk_add_f32 v[216:217], v[216:217], 1.0 op_sel_hi:[1,0] neg_lo:[1,0] neg_hi:[1,0]
	v_mov_b32_e32 v225, v64
	v_pk_mul_f32 v[68:69], v[216:217], v[68:69]
	v_pk_add_f32 v[62:63], v[62:63], 1.0 op_sel_hi:[1,0] neg_lo:[1,0] neg_hi:[1,0]
	s_waitcnt lgkmcnt(0)
	v_cndmask_b32_e64 v3, 1.0, v224, s[6:7]
	v_pk_mul_f32 v[216:217], v[54:55], v[224:225]
	v_pk_mul_f32 v[66:67], v[62:63], v[66:67]
	v_mul_f32_e32 v63, v3, v217
	s_mul_i32 s12, s2, 0x2200
	v_mul_f32_e32 v62, v5, v63
	v_mul_f32_e32 v55, v4, v62
	v_add3_u32 v3, v220, s12, v221
	v_mul_f32_e32 v54, v57, v55
	v_pk_add_f32 v[56:57], v[56:57], 1.0 op_sel_hi:[1,0] neg_lo:[1,0] neg_hi:[1,0]
	v_add_u32_e32 v213, 0x4800, v3
	v_pk_mul_f32 v[64:65], v[56:57], v[54:55]
	ds_read2_b64 v[54:57], v213 offset1:2
	v_pk_add_f32 v[4:5], v[4:5], 1.0 op_sel_hi:[1,0] neg_lo:[1,0] neg_hi:[1,0]
	v_add_u32_e32 v3, 0x5800, v3
	v_pk_mul_f32 v[4:5], v[4:5], v[62:63]
	v_cvt_pk_bf16_f32 v62, v64, v65
	v_cvt_pk_bf16_f32 v64, v68, v69
	v_cvt_pk_bf16_f32 v65, v66, v67
	ds_read2_b64 v[66:69], v3 offset0:32 offset1:34
	v_cvt_pk_bf16_f32 v63, v4, v5
	v_mul_f32_e32 v5, v52, v227
	v_mul_f32_e32 v4, v61, v5
	s_waitcnt lgkmcnt(1)
	v_mfma_f32_32x32x16_bf16 v[6:21], v[54:57], v[62:65], v[6:21]
	v_mul_f32_e32 v55, v60, v4
	v_mul_f32_e32 v54, v59, v55
	v_add_f32_e64 v56, -v58, 1.0
	v_add_f32_e64 v57, -v59, 1.0
	v_add_f32_e64 v60, -v60, 1.0
	v_add_f32_e64 v61, -v61, 1.0
	v_pk_mul_f32 v[58:59], v[56:57], v[54:55]
	ds_read2_b64 v[54:57], v213 offset0:4 offset1:6
	v_pk_mul_f32 v[4:5], v[60:61], v[4:5]
	s_waitcnt lgkmcnt(1)
	v_mfma_f32_32x32x16_bf16 v[22:37], v[66:69], v[62:65], v[22:37]
	ds_read2_b64 v[62:65], v3 offset0:36 offset1:38
	v_cvt_pk_bf16_f32 v58, v58, v59
	v_cvt_pk_bf16_f32 v59, v4, v5
	v_mul_f32_e32 v5, v39, v231
	v_cvt_pk_bf16_f32 v60, v234, v235
	v_cvt_pk_bf16_f32 v61, v232, v233
	v_mul_f32_e32 v4, v43, v5
	s_waitcnt lgkmcnt(1)
	v_mfma_f32_32x32x16_bf16 v[6:21], v[54:57], v[58:61], v[6:21]
	v_mul_f32_e32 v55, v42, v4
	v_mul_f32_e32 v54, v41, v55
	v_add_f32_e64 v40, -v40, 1.0
	v_add_f32_e64 v41, -v41, 1.0
	v_add_f32_e64 v42, -v42, 1.0
	v_add_f32_e64 v43, -v43, 1.0
	v_pk_mul_f32 v[40:41], v[40:41], v[54:55]
	ds_read2_b64 v[54:57], v213 offset0:8 offset1:10
	v_pk_mul_f32 v[4:5], v[42:43], v[4:5]
	s_waitcnt lgkmcnt(1)
	v_mfma_f32_32x32x16_bf16 v[22:37], v[62:65], v[58:61], v[22:37]
	ds_read2_b64 v[58:61], v3 offset0:40 offset1:42
	v_cvt_pk_bf16_f32 v40, v40, v41
	v_cvt_pk_bf16_f32 v41, v4, v5
	v_cndmask_b32_e64 v4, 1.0, v212, s[6:7]
	v_mul_f32_e32 v5, v4, v53
	v_cvt_pk_bf16_f32 v42, v238, v239
	v_cvt_pk_bf16_f32 v43, v70, v71
	v_mul_f32_e32 v4, v47, v5
	s_waitcnt lgkmcnt(1)
	v_mfma_f32_32x32x16_bf16 v[6:21], v[54:57], v[40:43], v[6:21]
	v_mul_f32_e32 v57, v46, v4
	v_mul_f32_e32 v56, v45, v57
	v_add_f32_e64 v44, -v44, 1.0
	v_add_f32_e64 v45, -v45, 1.0
	ds_read2_b64 v[52:55], v213 offset0:12 offset1:14
	v_mul_f32_e32 v213, v216, v217
	s_waitcnt lgkmcnt(1)
	v_mfma_f32_32x32x16_bf16 v[22:37], v[58:61], v[40:43], v[22:37]
	v_mul_f32_e64 v40, v44, v56
	v_mul_f32_e64 v41, v45, v57
	v_add_f32_e64 v42, -v46, 1.0
	v_add_f32_e64 v43, -v47, 1.0
	ds_read2_b64 v[44:47], v3 offset0:44 offset1:46
	v_pk_mul_f32 v[4:5], v[42:43], v[4:5]
	v_cvt_pk_bf16_f32 v40, v40, v41
	v_cvt_pk_bf16_f32 v41, v4, v5
	v_cvt_pk_bf16_f32 v42, v48, v49
	v_cvt_pk_bf16_f32 v43, v50, v51
	s_waitcnt lgkmcnt(1)
	s_nop 0
	v_mfma_f32_32x32x16_bf16 v[6:21], v[52:55], v[40:43], v[6:21]
	s_waitcnt lgkmcnt(0)
	v_mfma_f32_32x32x16_bf16 v[22:37], v[44:47], v[40:43], v[22:37]
